# pre-run CU sets moved to CUs that do not also run the L2 warm-up helper (k = 9.. instead of 1..)
# baseline (speedup 1.0000x reference)
;     __host__ __device__ bool next(int i, Unit& u) const {
;     ...
;         int wgid = (int)L; { const int q = nwg / NXCD, r = nwg % NXCD, xcd = wgid % NXCD, off = wgid / NXCD; wgid = (xcd < r ? xcd * (q + 1) : r * (q + 1) + (xcd - r) * q) + off; }
;         const int nig = WGM * nN, gid = wgid / nig, fm = gid * WGM, gsz = (nM - fm) < WGM ? (nM - fm) : WGM;
;         u.pm = fm + ((wgid % nig) % gsz); u.pn = (wgid % nig) / gsz; return true;
.Lpre_real:
	s_movk_i32 s98, 0xb00
	s_and_b32 s100, s96, 7
	s_cmp_gt_u32 s100, 2
	s_cbranch_scc1 .Lpre_done
	s_lshr_b32 s101, s96, 3
	s_add_i32 s101, s101, -9
	s_cmp_gt_u32 s101, 21
	s_cbranch_scc1 .Lpre_done
	s_mul_i32 s101, s101, 3
	s_add_i32 s101, s101, s100
	s_and_b32 s100, s101, 7
	s_lshr_b32 s101, s101, 3
	s_addk_i32 s101, 0x160
	s_mul_i32 s2, s100, 0x168
	s_min_u32 s100, s100, 2
	s_add_i32 s2, s2, s100
	s_add_i32 s2, s2, s101
	s_mul_hi_u32 s23, s2, 0x2e8ba2e9
	s_lshr_b32 s23, s23, 5
	s_mul_i32 s100, s23, 0xb0
	s_sub_i32 s100, s2, s100
	s_lshl_b32 s23, s23, 3
	s_cmp_eq_u32 s23, 0x80
	s_cbranch_scc1 .Lpre_g16
	s_and_b32 s2, s100, 7
	s_add_i32 s2, s2, s23
	s_lshr_b32 s23, s100, 3
	s_branch .Lpre_done

;     __host__ __device__ bool next(int i, Unit& u) const {
;     ...
;         int wgid = (int)L; { const int q = nwg / NXCD, r = nwg % NXCD, xcd = wgid % NXCD, off = wgid / NXCD; wgid = (xcd < r ? xcd * (q + 1) : r * (q + 1) + (xcd - r) * q) + off; }
;         const int nig = WGM * nN, gid = wgid / nig, fm = gid * WGM, gsz = (nM - fm) < WGM ? (nM - fm) : WGM;
;         u.pm = fm + ((wgid % nig) % gsz); u.pn = (wgid % nig) / gsz; return true;
.Lpre1_real:
	s_cmp_eq_u32 s83, 6
	s_cbranch_scc0 .Lpre1_done
	s_movk_i32 s98, 0x500
	s_and_b32 s100, s96, 7
	s_cmp_lg_u32 s100, 0
	s_cbranch_scc1 .Lpre1_done
	s_lshr_b32 s101, s96, 3
	s_add_i32 s101, s101, -9
	s_cmp_gt_u32 s101, 19
	s_cbranch_scc1 .Lpre1_done
	s_and_b32 s100, s101, 7
	s_lshr_b32 s101, s101, 3
	s_addk_i32 s101, 0xa0
	s_mul_i32 s2, s100, 0xa2
	s_min_u32 s100, s100, 4
	s_add_i32 s2, s2, s100
	s_add_i32 s2, s2, s101
	s_mul_hi_u32 s63, s2, 0x66666667
	s_lshr_b32 s63, s63, 6
	s_mul_i32 s100, s63, 0xa0
	s_sub_i32 s100, s2, s100
	s_lshl_b32 s63, s63, 3
	s_cmp_eq_u32 s63, 0x40
	s_cbranch_scc1 .Lpre1_g8
	s_lshr_b32 s2, s100, 3
	s_and_b32 s100, s100, 7
	s_add_i32 s63, s63, s100
	s_branch .Lpre1_done

; __global__ void __launch_bounds__(512, 2) fwd_mega(Args a_) {
;     ...
;         int kind = 15, slab = 0;
;         if (ph == 0) kind = 0;
;         else if (ph <= 10) { const int q = (ph - 1) % 5; slab = (ph - 1) / 5; kind = q == 0 ? 1 : (q == 1 ? 14 : (q == 2 ? 2 : (q == 3 ? 3 : 4))); }
;         else if (ph == 11) kind = 5; else if (ph == 12) kind = 6;
;         else if (ph <= 26) { kind = 7 + (ph - 13) % 7; slab = (ph - 13) / 7; }
;         else if (ph == 27) { kind = 5; slab = 1; } else if (ph == 28) { kind = 6; slab = 1; }
.Lpre_chk:
	s_and_b32 s101, s96, 7
	s_cmp_gt_u32 s101, 2
	s_cbranch_scc1 .Lpre_none
	s_lshr_b32 s101, s96, 3
	s_add_i32 s101, s101, -9
	s_cmp_gt_u32 s101, 21
	s_cbranch_scc1 .Lpre_none
	s_mov_b32 s99, 1
	s_mov_b32 s65, 5
	s_mov_b32 s40, s100

; __global__ void __launch_bounds__(512, 2) fwd_mega(Args a_) {
;     ...
;         int kind = 15, slab = 0;
;         if (ph == 0) kind = 0;
;         else if (ph <= 10) { const int q = (ph - 1) % 5; slab = (ph - 1) / 5; kind = q == 0 ? 1 : (q == 1 ? 14 : (q == 2 ? 2 : (q == 3 ? 3 : 4))); }
;         else if (ph == 11) kind = 5; else if (ph == 12) kind = 6;
;         else if (ph <= 26) { kind = 7 + (ph - 13) % 7; slab = (ph - 13) / 7; }
;         else if (ph == 27) { kind = 5; slab = 1; } else if (ph == 28) { kind = 6; slab = 1; }
.Lpre_chk1:
	s_and_b32 s101, s96, 7
	s_cmp_lg_u32 s101, 0
	s_cbranch_scc1 .Lpre_none
	s_lshr_b32 s101, s96, 3
	s_add_i32 s101, s101, -9
	s_cmp_gt_u32 s101, 19
	s_cbranch_scc1 .Lpre_none
	s_mov_b32 s99, 1
	s_mov_b32 s65, 1
	s_mov_b32 s40, 1
	s_branch .Lpre_go
